# hyena ctx part rewritten by hand: all global loads issued up front, 256-tap ctx conv as f32 MFMA 32x32x2 Toeplitz product (verified elementwise vs old code in a separate self-check build)
# speedup vs baseline: 1.0059x; 1.0059x over previous
.LBB0_304:
	s_mov_b64 exec, -1
	v_readlane_b32 s6, v255, 29
	s_load_dwordx4 s[48:51], s[0:1], 0x50
	s_load_dwordx2 s[52:53], s[0:1], 0x98
	s_nop 3
	s_mul_i32 s7, s2, 0x4400
	s_lshl_b32 s8, s7, 1
	s_add_u32 s10, s64, 0x8f00000
	s_addc_u32 s11, s65, 0
	s_add_u32 s10, s10, s8
	s_addc_u32 s11, s11, 0
	s_add_u32 s10, s10, 0x8000
	s_addc_u32 s11, s11, 0
	s_add_u32 s12, s64, 0x11c00000
	s_addc_u32 s13, s65, 0
	s_add_u32 s12, s12, s7
	s_addc_u32 s13, s13, 0
	s_add_u32 s12, s12, 0x4000
	s_addc_u32 s13, s13, 0
	s_lshl_b32 s8, s2, 1
	s_add_u32 s16, s64, 0x10d00000
	s_addc_u32 s17, s65, 0
	s_add_u32 s16, s16, s8
	s_addc_u32 s17, s17, 0
	v_and_b32_e32 v8, 0xff, v208
	v_lshrrev_b32_e32 v9, 8, v208
	v_and_b32_e32 v10, 31, v208
	v_bfe_u32 v11, v208, 5, 1
	v_lshrrev_b32_e32 v0, 6, v208
	s_nop 0
	v_readfirstlane_b32 s14, v0
	v_lshlrev_b32_e32 v2, 2, v8
	global_load_dword v14, v2, s[12:13]
	v_add_u32_e32 v3, 0x880000, v2
	global_load_dword v15, v3, s[12:13]
	v_add_u32_e32 v3, 0x1100000, v2
	global_load_dword v16, v3, s[12:13]
	v_add_u32_e32 v3, 0x1980000, v2
	global_load_dword v17, v3, s[12:13]
	v_lshlrev_b32_e32 v2, 1, v208
	global_load_ushort v18, v2, s[10:11] offset:-2
	global_load_ushort v19, v2, s[10:11]
	global_load_ushort v20, v2, s[10:11] offset:2
	global_load_ushort v21, v2, s[10:11] offset:1022
	global_load_ushort v22, v2, s[10:11] offset:1024
	global_load_ushort v23, v2, s[10:11] offset:1026
	v_lshlrev_b32_e32 v3, 10, v9
	v_lshl_add_u32 v3, v8, 1, v3
	v_add_u32_e32 v4, 0x1100000, v3
	global_load_ushort v24, v4, s[10:11] offset:-2
	global_load_ushort v25, v4, s[10:11]
	global_load_ushort v26, v4, s[10:11] offset:2
	global_load_ushort v27, v4, s[10:11] offset:510
	global_load_ushort v28, v4, s[10:11] offset:512
	global_load_ushort v29, v4, s[10:11] offset:514
	v_add_u32_e32 v4, 0x2200000, v3
	global_load_ushort v30, v4, s[10:11] offset:-2
	global_load_ushort v31, v4, s[10:11]
	global_load_ushort v32, v4, s[10:11] offset:2
	global_load_ushort v33, v4, s[10:11] offset:510
	global_load_ushort v34, v4, s[10:11] offset:512
	global_load_ushort v35, v4, s[10:11] offset:514
	s_waitcnt lgkmcnt(0)
	s_mul_i32 s8, s6, 0x4800
	s_lshl_b32 s9, s2, 2
	s_add_u32 s48, s48, s8
	s_addc_u32 s49, s49, 0
	s_add_u32 s48, s48, s9
	s_addc_u32 s49, s49, 0
	s_mul_i32 s8, s6, 0x1800
	s_add_u32 s50, s50, s8
	s_addc_u32 s51, s51, 0
	s_add_u32 s50, s50, s9
	s_addc_u32 s51, s51, 0
	s_lshl_b32 s8, s6, 12
	s_add_u32 s52, s52, s8
	s_addc_u32 s53, s53, 0
	s_add_u32 s52, s52, s9
	s_addc_u32 s53, s53, 0
	global_load_dword v36, v1, s[48:49]
	v_mov_b32_e32 v4, 0x1800
	global_load_dword v37, v4, s[48:49]
	v_mov_b32_e32 v4, 0x3000
	global_load_dword v38, v4, s[48:49]
	global_load_dword v39, v1, s[50:51]
	global_load_dword v40, v1, s[48:49] offset:2048
	v_mov_b32_e32 v4, 0x2000
	global_load_dword v41, v4, s[48:49]
	v_mov_b32_e32 v4, 0x3800
	global_load_dword v42, v4, s[48:49]
	global_load_dword v43, v1, s[50:51] offset:2048
	global_load_dword v44, v1, s[52:53]
	v_mov_b32_e32 v4, 0x1000
	global_load_dword v45, v4, s[48:49]
	v_mov_b32_e32 v4, 0x2800
	global_load_dword v46, v4, s[48:49]
	v_mov_b32_e32 v4, 0x4000
	global_load_dword v47, v4, s[48:49]
	v_mov_b32_e32 v4, 0x1000
	global_load_dword v48, v4, s[50:51]
	global_load_dword v49, v1, s[52:53] offset:2048
	v_mov_b32_e32 v4, 0
	v_mov_b32_e32 v5, 0
	v_mov_b32_e32 v6, 0
	v_mov_b32_e32 v7, 0
	v_mul_u32_u24_e32 v0, 48, v208
	v_add_u32_e32 v0, 0x1000, v0
	ds_write_b128 v0, v[4:7]
	ds_write_b128 v0, v[4:7] offset:16
	ds_write_b128 v0, v[4:7] offset:32
	v_sub_u32_e32 v56, v10, v11
	v_lshlrev_b32_e32 v56, 2, v56
	v_add_u32_e32 v56, 900, v56
	v_lshrrev_b32_e32 v2, 3, v10
	v_mul_u32_u24_e32 v2, 744, v2
	v_and_b32_e32 v3, 7, v10
	v_mad_u32_u24 v2, v3, 33, v2
	v_add_u32_e32 v2, v2, v11
	v_lshlrev_b32_e32 v57, 2, v2
	v_add_u32_e32 v57, 924, v57
	v_mul_u32_u24_e32 v2, 33, v10
	v_lshl_add_u32 v2, v11, 2, v2
	v_lshlrev_b32_e32 v58, 2, v2
	s_mul_i32 s8, s14, 4224
	s_add_i32 s8, s8, 0x8000
	v_add_u32_e32 v58, s8, v58
	v_lshrrev_b32_e32 v2, 5, v8
	v_lshl_add_u32 v2, v9, 4, v2
	v_mul_u32_u24_e32 v2, 33, v2
	v_and_b32_e32 v3, 31, v8
	v_add_u32_e32 v2, v2, v3
	v_lshlrev_b32_e32 v59, 2, v2
	v_add_u32_e32 v59, 0x8000, v59
	v_lshrrev_b32_e32 v2, 5, v8
	v_add_u32_e32 v2, 7, v2
	v_mul_u32_u24_e32 v2, 33, v2
	v_add_u32_e32 v2, v2, v3
	v_mul_u32_u24_e32 v4, 1488, v9
	v_add_u32_e32 v2, v2, v4
	v_lshlrev_b32_e32 v60, 2, v2
	v_mul_u32_u24_e32 v4, 744, v9
	v_sub_u32_e32 v2, v2, v4
	v_lshlrev_b32_e32 v61, 2, v2
	v_cvt_f32_i32_e32 v2, s2
	v_mov_b32_e32 v3, 0xc0447cbd
	v_fmamk_f32 v12, v2, 0xbcc4df2d, v3
	v_and_b32_e32 v0, 0x7fffffff, v12
	s_mov_b32 s46, 0x437f0000
	v_div_scale_f32 v2, s[8:9], s46, s46, v0
	v_rcp_f32_e32 v3, v2
	v_div_scale_f32 v0, vcc, v0, s46, v0
	v_fma_f32 v4, -v2, v3, 1.0
	v_fmac_f32_e32 v3, v4, v3
	v_mul_f32_e32 v4, v0, v3
	v_fma_f32 v5, -v2, v4, v0
	v_fmac_f32_e32 v4, v5, v3
	v_fma_f32 v0, -v2, v4, v0
	v_div_fmas_f32 v0, v0, v3, v4
	v_div_fixup_f32 v0, v0, s46, |v12|
	v_cvt_f32_i32_e32 v2, v8
	v_mul_f32_e32 v0, v0, v2
	v_mul_f32_e32 v0, 0xbfb8aa3b, v0
	v_exp_f32_e32 v13, v0
	v_cmp_ne_u32_e64 s[54:55], 0, v8
	s_movk_i32 s9, 0xff
	v_cmp_ne_u32_e64 s[46:47], s9, v8
	s_waitcnt vmcnt(0)
	v_mul_f32_e32 v14, v14, v13
	v_mul_f32_e32 v15, v15, v13
	v_mul_f32_e32 v16, v16, v13
	v_mul_f32_e32 v17, v17, v13
	v_cndmask_b32_e64 v15, 0, v15, s[54:55]
	v_cndmask_b32_e64 v17, 0, v17, s[54:55]
	v_lshlrev_b32_e32 v2, 2, v8
	v_add_u32_e32 v3, 1020, v2
	v_sub_u32_e32 v4, 1020, v2
	v_mov_b32_e32 v5, 0x7fc
	v_cndmask_b32_e64 v4, v5, v4, s[54:55]
	v_cmp_gt_u32_e32 vcc, 0x100, v208
	s_and_saveexec_b64 s[8:9], vcc
	ds_write_b32 v3, v14 offset:0
	ds_write_b32 v4, v15 offset:0
	ds_write_b32 v3, v16 offset:2048
	ds_write_b32 v4, v17 offset:2048
	s_mov_b64 exec, s[8:9]
	v_mul_f32_e32 v54, v14, v14
	v_fmac_f32_e32 v54, v15, v15
	v_mul_f32_e32 v55, v16, v16
	v_fmac_f32_e32 v55, v17, v17
	v_cndmask_b32_e32 v54, 0, v54, vcc
	v_cndmask_b32_e32 v55, 0, v55, vcc
	v_lshlrev_b32_e32 v18, 16, v18
	v_lshlrev_b32_e32 v19, 16, v19
	v_lshlrev_b32_e32 v20, 16, v20
	v_cndmask_b32_e64 v18, 0, v18, s[54:55]
	v_cndmask_b32_e64 v20, 0, v20, s[46:47]
	v_fma_f32 v62, v37, v19, v39
	v_fmac_f32_e32 v62, v36, v18
	v_fmac_f32_e32 v62, v38, v20
	v_lshlrev_b32_e32 v21, 16, v21
	v_lshlrev_b32_e32 v22, 16, v22
	v_lshlrev_b32_e32 v23, 16, v23
	v_cndmask_b32_e64 v21, 0, v21, s[54:55]
	v_cndmask_b32_e64 v23, 0, v23, s[46:47]
	v_fma_f32 v63, v37, v22, v39
	v_fmac_f32_e32 v63, v36, v21
	v_fmac_f32_e32 v63, v38, v23
	v_lshlrev_b32_e32 v24, 16, v24
	v_lshlrev_b32_e32 v25, 16, v25
	v_lshlrev_b32_e32 v26, 16, v26
	v_cndmask_b32_e64 v24, 0, v24, s[54:55]
	v_cndmask_b32_e64 v26, 0, v26, s[46:47]
	v_fma_f32 v50, v41, v25, v43
	v_fmac_f32_e32 v50, v40, v24
	v_fmac_f32_e32 v50, v42, v26
	v_lshlrev_b32_e32 v27, 16, v27
	v_lshlrev_b32_e32 v28, 16, v28
	v_lshlrev_b32_e32 v29, 16, v29
	v_cndmask_b32_e64 v27, 0, v27, s[54:55]
	v_cndmask_b32_e64 v29, 0, v29, s[46:47]
	v_fma_f32 v51, v41, v28, v43
	v_fmac_f32_e32 v51, v40, v27
	v_fmac_f32_e32 v51, v42, v29
	v_lshlrev_b32_e32 v30, 16, v30
	v_lshlrev_b32_e32 v31, 16, v31
	v_lshlrev_b32_e32 v32, 16, v32
	v_cndmask_b32_e64 v30, 0, v30, s[54:55]
	v_cndmask_b32_e64 v32, 0, v32, s[46:47]
	v_fma_f32 v52, v46, v31, v48
	v_fmac_f32_e32 v52, v45, v30
	v_fmac_f32_e32 v52, v47, v32
	v_lshlrev_b32_e32 v33, 16, v33
	v_lshlrev_b32_e32 v34, 16, v34
	v_lshlrev_b32_e32 v35, 16, v35
	v_cndmask_b32_e64 v33, 0, v33, s[54:55]
	v_cndmask_b32_e64 v35, 0, v35, s[46:47]
	v_fma_f32 v53, v46, v34, v48
	v_fmac_f32_e32 v53, v45, v33
	v_fmac_f32_e32 v53, v47, v35
	ds_swizzle_b32 v2, v54 offset:0x41f
	ds_swizzle_b32 v3, v55 offset:0x41f
	s_waitcnt lgkmcnt(0)
	v_add_f32_e32 v54, v54, v2
	v_add_f32_e32 v55, v55, v3
	ds_swizzle_b32 v2, v54 offset:0x81f
	ds_swizzle_b32 v3, v55 offset:0x81f
	s_waitcnt lgkmcnt(0)
	v_add_f32_e32 v54, v54, v2
	v_add_f32_e32 v55, v55, v3
	ds_swizzle_b32 v2, v54 offset:0x101f
	ds_swizzle_b32 v3, v55 offset:0x101f
	s_waitcnt lgkmcnt(0)
	v_add_f32_e32 v54, v54, v2
	v_add_f32_e32 v55, v55, v3
	ds_swizzle_b32 v2, v54 offset:0x201f
	ds_swizzle_b32 v3, v55 offset:0x201f
	s_waitcnt lgkmcnt(0)
	v_add_f32_e32 v54, v54, v2
	v_add_f32_e32 v55, v55, v3
	ds_swizzle_b32 v2, v54 offset:0x401f
	ds_swizzle_b32 v3, v55 offset:0x401f
	s_waitcnt lgkmcnt(0)
	v_add_f32_e32 v54, v54, v2
	v_add_f32_e32 v55, v55, v3
	s_nop 1
	v_readlane_b32 s8, v54, 0
	v_readlane_b32 s9, v54, 32
	v_readlane_b32 s46, v55, 0
	v_readlane_b32 s47, v55, 32
	s_nop 3
	v_mov_b32_e32 v2, s8
	v_add_f32_e32 v2, s9, v2
	v_mov_b32_e32 v3, s46
	v_add_f32_e32 v3, s47, v3
	s_lshl_b32 s8, s14, 2
	s_add_i32 s8, s8, 0x10800
	v_mov_b32_e32 v4, s8
	ds_write_b32 v4, v2
	ds_write_b32 v4, v3 offset:32
	s_waitcnt lgkmcnt(0)
	s_barrier
	ds_write_b32 v61, v62 offset:4096
	ds_write_b32 v61, v63 offset:10048
	s_waitcnt lgkmcnt(0)
	s_barrier
	v_mov_b32_e32 v2, 0x10800
	ds_read_b128 v[4:7], v2
	ds_read_b128 v[18:21], v2 offset:16
	ds_read_b128 v[22:25], v2 offset:32
	ds_read_b128 v[26:29], v2 offset:48
	s_waitcnt lgkmcnt(0)
	v_add_f32_e32 v0, 0, v4
	v_add_f32_e32 v0, v0, v5
	v_add_f32_e32 v0, v0, v6
	v_add_f32_e32 v0, v0, v7
	v_add_f32_e32 v0, v0, v18
	v_add_f32_e32 v0, v0, v19
	v_add_f32_e32 v0, v0, v20
	v_add_f32_e32 v0, v0, v21
	v_add_f32_e32 v0, 0x358637bd, v0
	v_mul_f32_e32 v2, 0x4f800000, v0
	v_cmp_gt_f32_e32 vcc, s23, v0
	s_nop 1
	v_cndmask_b32_e32 v0, v0, v2, vcc
	v_sqrt_f32_e32 v2, v0
	s_nop 0
	v_add_u32_e32 v3, -1, v2
	v_fma_f32 v31, -v3, v2, v0
	v_add_u32_e32 v30, 1, v2
	v_cmp_ge_f32_e64 s[8:9], 0, v31
	s_nop 1
	v_cndmask_b32_e64 v3, v2, v3, s[8:9]
	v_fma_f32 v2, -v30, v2, v0
	v_cmp_lt_f32_e64 s[8:9], 0, v2
	s_nop 1
	v_cndmask_b32_e64 v2, v3, v30, s[8:9]
	v_mul_f32_e32 v3, 0x37800000, v2
	v_cndmask_b32_e32 v2, v2, v3, vcc
	v_cmp_class_f32_e32 vcc, v0, v210
	s_nop 1
	v_cndmask_b32_e32 v0, v2, v0, vcc
	v_div_scale_f32 v30, s[8:9], v0, v0, 1.0
	v_rcp_f32_e32 v31, v30
	v_div_scale_f32 v32, vcc, 1.0, v0, 1.0
	v_fma_f32 v2, -v30, v31, 1.0
	v_fmac_f32_e32 v31, v2, v31
	v_mul_f32_e32 v33, v32, v31
	v_fma_f32 v2, -v30, v33, v32
	v_fmac_f32_e32 v33, v2, v31
	v_fma_f32 v30, -v30, v33, v32
	v_div_fmas_f32 v30, v30, v31, v33
	v_div_fixup_f32 v54, v30, v0, 1.0
	v_add_f32_e32 v0, 0, v22
	v_add_f32_e32 v0, v0, v23
	v_add_f32_e32 v0, v0, v24
	v_add_f32_e32 v0, v0, v25
	v_add_f32_e32 v0, v0, v26
	v_add_f32_e32 v0, v0, v27
	v_add_f32_e32 v0, v0, v28
	v_add_f32_e32 v0, v0, v29
	v_add_f32_e32 v0, 0x358637bd, v0
	v_mul_f32_e32 v2, 0x4f800000, v0
	v_cmp_gt_f32_e32 vcc, s23, v0
	s_nop 1
	v_cndmask_b32_e32 v0, v0, v2, vcc
	v_sqrt_f32_e32 v2, v0
	s_nop 0
	v_add_u32_e32 v3, -1, v2
	v_fma_f32 v31, -v3, v2, v0
	v_add_u32_e32 v30, 1, v2
	v_cmp_ge_f32_e64 s[8:9], 0, v31
	s_nop 1
	v_cndmask_b32_e64 v3, v2, v3, s[8:9]
	v_fma_f32 v2, -v30, v2, v0
	v_cmp_lt_f32_e64 s[8:9], 0, v2
	s_nop 1
	v_cndmask_b32_e64 v2, v3, v30, s[8:9]
	v_mul_f32_e32 v3, 0x37800000, v2
	v_cndmask_b32_e32 v2, v2, v3, vcc
	v_cmp_class_f32_e32 vcc, v0, v210
	s_nop 1
	v_cndmask_b32_e32 v0, v2, v0, vcc
	v_div_scale_f32 v30, s[8:9], v0, v0, 1.0
	v_rcp_f32_e32 v31, v30
	v_div_scale_f32 v32, vcc, 1.0, v0, 1.0
	v_fma_f32 v2, -v30, v31, 1.0
	v_fmac_f32_e32 v31, v2, v31
	v_mul_f32_e32 v33, v32, v31
	v_fma_f32 v2, -v30, v33, v32
	v_fmac_f32_e32 v33, v2, v31
	v_fma_f32 v30, -v30, v33, v32
	v_div_fmas_f32 v30, v30, v31, v33
	v_div_fixup_f32 v55, v30, v0, 1.0
	s_lshl_b32 s8, s14, 8
	s_add_i32 s8, s8, -896
	s_mul_i32 s9, s14, -264
	s_add_i32 s9, s9, 924
	v_add_u32_e32 v2, s8, v56
	v_add_u32_e32 v3, s9, v57
	ds_read_b32 v80, v2 offset:120
	ds_read_b32 v96, v3 offset:4096
	ds_read_b32 v81, v2 offset:112
	ds_read_b32 v97, v3 offset:4104
	ds_read_b32 v82, v2 offset:104
	ds_read_b32 v98, v3 offset:4112
	ds_read_b32 v83, v2 offset:96
	ds_read_b32 v99, v3 offset:4120
	ds_read_b32 v84, v2 offset:88
	ds_read_b32 v100, v3 offset:4128
	ds_read_b32 v85, v2 offset:80
	ds_read_b32 v101, v3 offset:4136
	ds_read_b32 v86, v2 offset:72
	ds_read_b32 v102, v3 offset:4144
	ds_read_b32 v87, v2 offset:64
	ds_read_b32 v103, v3 offset:4152
	ds_read_b32 v88, v2 offset:56
	ds_read_b32 v104, v3 offset:4160
	ds_read_b32 v89, v2 offset:48
	ds_read_b32 v105, v3 offset:4168
	ds_read_b32 v90, v2 offset:40
	ds_read_b32 v106, v3 offset:4176
	ds_read_b32 v91, v2 offset:32
	ds_read_b32 v107, v3 offset:4184
	ds_read_b32 v92, v2 offset:24
	ds_read_b32 v108, v3 offset:4192
	ds_read_b32 v93, v2 offset:16
	ds_read_b32 v109, v3 offset:4200
	ds_read_b32 v94, v2 offset:8
	ds_read_b32 v110, v3 offset:4208
	ds_read_b32 v95, v2 offset:0
	ds_read_b32 v111, v3 offset:4216
	s_cmp_eq_u32 s14, 7
	s_cbranch_scc1 .Lhc_o0_skipq2
	v_add_u32_e32 v2, 0x80, v2
	v_add_u32_e32 v3, 0xffffff7c, v3
	ds_read_b32 v112, v2 offset:120
	ds_read_b32 v128, v3 offset:4096
	ds_read_b32 v113, v2 offset:112
	ds_read_b32 v129, v3 offset:4104
	ds_read_b32 v114, v2 offset:104
	ds_read_b32 v130, v3 offset:4112
	ds_read_b32 v115, v2 offset:96
	ds_read_b32 v131, v3 offset:4120
	ds_read_b32 v116, v2 offset:88
	ds_read_b32 v132, v3 offset:4128
	ds_read_b32 v117, v2 offset:80
	ds_read_b32 v133, v3 offset:4136
	ds_read_b32 v118, v2 offset:72
	ds_read_b32 v134, v3 offset:4144
	ds_read_b32 v119, v2 offset:64
	ds_read_b32 v135, v3 offset:4152
	ds_read_b32 v120, v2 offset:56
	ds_read_b32 v136, v3 offset:4160
	ds_read_b32 v121, v2 offset:48
	ds_read_b32 v137, v3 offset:4168
	ds_read_b32 v122, v2 offset:40
	ds_read_b32 v138, v3 offset:4176
	ds_read_b32 v123, v2 offset:32
	ds_read_b32 v139, v3 offset:4184
	ds_read_b32 v124, v2 offset:24
	ds_read_b32 v140, v3 offset:4192
	ds_read_b32 v125, v2 offset:16
	ds_read_b32 v141, v3 offset:4200
	ds_read_b32 v126, v2 offset:8
	ds_read_b32 v142, v3 offset:4208
	ds_read_b32 v127, v2 offset:0
	ds_read_b32 v143, v3 offset:4216
.Lhc_o0_skipq2:
	s_waitcnt lgkmcnt(0)
	v_mfma_f32_32x32x2_f32 v[64:79], v80, v96, 0
	v_mfma_f32_32x32x2_f32 v[64:79], v81, v97, v[64:79]
	v_mfma_f32_32x32x2_f32 v[64:79], v82, v98, v[64:79]
	v_mfma_f32_32x32x2_f32 v[64:79], v83, v99, v[64:79]
	v_mfma_f32_32x32x2_f32 v[64:79], v84, v100, v[64:79]
	v_mfma_f32_32x32x2_f32 v[64:79], v85, v101, v[64:79]
	v_mfma_f32_32x32x2_f32 v[64:79], v86, v102, v[64:79]
	v_mfma_f32_32x32x2_f32 v[64:79], v87, v103, v[64:79]
	v_mfma_f32_32x32x2_f32 v[64:79], v88, v104, v[64:79]
	v_mfma_f32_32x32x2_f32 v[64:79], v89, v105, v[64:79]
	v_mfma_f32_32x32x2_f32 v[64:79], v90, v106, v[64:79]
	v_mfma_f32_32x32x2_f32 v[64:79], v91, v107, v[64:79]
	v_mfma_f32_32x32x2_f32 v[64:79], v92, v108, v[64:79]
	v_mfma_f32_32x32x2_f32 v[64:79], v93, v109, v[64:79]
	v_mfma_f32_32x32x2_f32 v[64:79], v94, v110, v[64:79]
	v_mfma_f32_32x32x2_f32 v[64:79], v95, v111, v[64:79]
	s_cbranch_scc1 .Lhc_o0_q2done
	v_mfma_f32_32x32x2_f32 v[64:79], v112, v128, v[64:79]
	v_mfma_f32_32x32x2_f32 v[64:79], v113, v129, v[64:79]
	v_mfma_f32_32x32x2_f32 v[64:79], v114, v130, v[64:79]
	v_mfma_f32_32x32x2_f32 v[64:79], v115, v131, v[64:79]
	v_mfma_f32_32x32x2_f32 v[64:79], v116, v132, v[64:79]
	v_mfma_f32_32x32x2_f32 v[64:79], v117, v133, v[64:79]
	v_mfma_f32_32x32x2_f32 v[64:79], v118, v134, v[64:79]
	v_mfma_f32_32x32x2_f32 v[64:79], v119, v135, v[64:79]
	v_mfma_f32_32x32x2_f32 v[64:79], v120, v136, v[64:79]
	v_mfma_f32_32x32x2_f32 v[64:79], v121, v137, v[64:79]
	v_mfma_f32_32x32x2_f32 v[64:79], v122, v138, v[64:79]
	v_mfma_f32_32x32x2_f32 v[64:79], v123, v139, v[64:79]
	v_mfma_f32_32x32x2_f32 v[64:79], v124, v140, v[64:79]
	v_mfma_f32_32x32x2_f32 v[64:79], v125, v141, v[64:79]
	v_mfma_f32_32x32x2_f32 v[64:79], v126, v142, v[64:79]
	v_mfma_f32_32x32x2_f32 v[64:79], v127, v143, v[64:79]
.Lhc_o0_q2done:
	s_nop 15
	s_nop 3
	ds_write_b32 v58, v64 offset:0
	ds_write_b32 v58, v65 offset:4
	ds_write_b32 v58, v66 offset:8
	ds_write_b32 v58, v67 offset:12
	ds_write_b32 v58, v68 offset:32
	ds_write_b32 v58, v69 offset:36
	ds_write_b32 v58, v70 offset:40
	ds_write_b32 v58, v71 offset:44
	ds_write_b32 v58, v72 offset:64
	ds_write_b32 v58, v73 offset:68
	ds_write_b32 v58, v74 offset:72
	ds_write_b32 v58, v75 offset:76
	ds_write_b32 v58, v76 offset:96
	ds_write_b32 v58, v77 offset:100
	ds_write_b32 v58, v78 offset:104
	ds_write_b32 v58, v79 offset:108
	s_waitcnt lgkmcnt(0)
	s_barrier
	ds_read_b32 v144, v59 offset:0
	ds_read_b32 v152, v59 offset:1056
	ds_read_b32 v145, v59 offset:4224
	ds_read_b32 v153, v59 offset:5280
	ds_read_b32 v146, v59 offset:8448
	ds_read_b32 v154, v59 offset:9504
	ds_read_b32 v147, v59 offset:12672
	ds_read_b32 v155, v59 offset:13728
	ds_read_b32 v148, v59 offset:16896
	ds_read_b32 v156, v59 offset:17952
	ds_read_b32 v149, v59 offset:21120
	ds_read_b32 v157, v59 offset:22176
	ds_read_b32 v150, v59 offset:25344
	ds_read_b32 v158, v59 offset:26400
	ds_read_b32 v151, v59 offset:29568
	ds_read_b32 v159, v59 offset:30624
	ds_read_b32 v62, v60 offset:4096
	ds_read_b32 v63, v60 offset:7072
	s_waitcnt lgkmcnt(0)
	v_add_f32_e32 v144, v144, v145
	v_add_f32_e32 v152, v152, v153
	v_add_f32_e32 v144, v144, v146
	v_add_f32_e32 v152, v152, v154
	v_add_f32_e32 v144, v144, v147
	v_add_f32_e32 v152, v152, v155
	v_add_f32_e32 v144, v144, v148
	v_add_f32_e32 v152, v152, v156
	v_add_f32_e32 v144, v144, v149
	v_add_f32_e32 v152, v152, v157
	v_add_f32_e32 v144, v144, v150
	v_add_f32_e32 v152, v152, v158
	v_add_f32_e32 v144, v144, v151
	v_add_f32_e32 v152, v152, v159
	v_mul_f32_e32 v2, v44, v62
	v_mul_f32_e32 v3, v44, v63
	v_fmac_f32_e32 v2, v54, v144
	v_fmac_f32_e32 v3, v54, v152
	v_mul_f32_e32 v62, v50, v2
	v_mul_f32_e32 v63, v51, v3
	ds_write_b32 v60, v62 offset:16384
	ds_write_b32 v60, v63 offset:19360
	s_waitcnt lgkmcnt(0)
	s_barrier
	v_add_u32_e32 v2, s8, v56
	v_add_u32_e32 v3, s9, v57
	ds_read_b32 v80, v2 offset:2168
	ds_read_b32 v96, v3 offset:16384
	ds_read_b32 v81, v2 offset:2160
	ds_read_b32 v97, v3 offset:16392
	ds_read_b32 v82, v2 offset:2152
	ds_read_b32 v98, v3 offset:16400
	ds_read_b32 v83, v2 offset:2144
	ds_read_b32 v99, v3 offset:16408
	ds_read_b32 v84, v2 offset:2136
	ds_read_b32 v100, v3 offset:16416
	ds_read_b32 v85, v2 offset:2128
	ds_read_b32 v101, v3 offset:16424
	ds_read_b32 v86, v2 offset:2120
	ds_read_b32 v102, v3 offset:16432
	ds_read_b32 v87, v2 offset:2112
	ds_read_b32 v103, v3 offset:16440
	ds_read_b32 v88, v2 offset:2104
	ds_read_b32 v104, v3 offset:16448
	ds_read_b32 v89, v2 offset:2096
	ds_read_b32 v105, v3 offset:16456
	ds_read_b32 v90, v2 offset:2088
	ds_read_b32 v106, v3 offset:16464
	ds_read_b32 v91, v2 offset:2080
	ds_read_b32 v107, v3 offset:16472
	ds_read_b32 v92, v2 offset:2072
	ds_read_b32 v108, v3 offset:16480
	ds_read_b32 v93, v2 offset:2064
	ds_read_b32 v109, v3 offset:16488
	ds_read_b32 v94, v2 offset:2056
	ds_read_b32 v110, v3 offset:16496
	ds_read_b32 v95, v2 offset:2048
	ds_read_b32 v111, v3 offset:16504
	s_cmp_eq_u32 s14, 7
	s_cbranch_scc1 .Lhc_o1_skipq2
	v_add_u32_e32 v2, 0x80, v2
	v_add_u32_e32 v3, 0xffffff7c, v3
	ds_read_b32 v112, v2 offset:2168
	ds_read_b32 v128, v3 offset:16384
	ds_read_b32 v113, v2 offset:2160
	ds_read_b32 v129, v3 offset:16392
	ds_read_b32 v114, v2 offset:2152
	ds_read_b32 v130, v3 offset:16400
	ds_read_b32 v115, v2 offset:2144
	ds_read_b32 v131, v3 offset:16408
	ds_read_b32 v116, v2 offset:2136
	ds_read_b32 v132, v3 offset:16416
	ds_read_b32 v117, v2 offset:2128
	ds_read_b32 v133, v3 offset:16424
	ds_read_b32 v118, v2 offset:2120
	ds_read_b32 v134, v3 offset:16432
	ds_read_b32 v119, v2 offset:2112
	ds_read_b32 v135, v3 offset:16440
	ds_read_b32 v120, v2 offset:2104
	ds_read_b32 v136, v3 offset:16448
	ds_read_b32 v121, v2 offset:2096
	ds_read_b32 v137, v3 offset:16456
	ds_read_b32 v122, v2 offset:2088
	ds_read_b32 v138, v3 offset:16464
	ds_read_b32 v123, v2 offset:2080
	ds_read_b32 v139, v3 offset:16472
	ds_read_b32 v124, v2 offset:2072
	ds_read_b32 v140, v3 offset:16480
	ds_read_b32 v125, v2 offset:2064
	ds_read_b32 v141, v3 offset:16488
	ds_read_b32 v126, v2 offset:2056
	ds_read_b32 v142, v3 offset:16496
	ds_read_b32 v127, v2 offset:2048
	ds_read_b32 v143, v3 offset:16504

.Lhc_o1_q2done:
	s_nop 15
	s_nop 3
	ds_write_b32 v58, v64 offset:0
	ds_write_b32 v58, v65 offset:4
	ds_write_b32 v58, v66 offset:8
	ds_write_b32 v58, v67 offset:12
	ds_write_b32 v58, v68 offset:32
	ds_write_b32 v58, v69 offset:36
	ds_write_b32 v58, v70 offset:40
	ds_write_b32 v58, v71 offset:44
	ds_write_b32 v58, v72 offset:64
	ds_write_b32 v58, v73 offset:68
	ds_write_b32 v58, v74 offset:72
	ds_write_b32 v58, v75 offset:76
	ds_write_b32 v58, v76 offset:96
	ds_write_b32 v58, v77 offset:100
	ds_write_b32 v58, v78 offset:104
	ds_write_b32 v58, v79 offset:108
	s_waitcnt lgkmcnt(0)
	s_barrier
	ds_read_b32 v144, v59 offset:0
	ds_read_b32 v152, v59 offset:1056
	ds_read_b32 v145, v59 offset:4224
	ds_read_b32 v153, v59 offset:5280
	ds_read_b32 v146, v59 offset:8448
	ds_read_b32 v154, v59 offset:9504
	ds_read_b32 v147, v59 offset:12672
	ds_read_b32 v155, v59 offset:13728
	ds_read_b32 v148, v59 offset:16896
	ds_read_b32 v156, v59 offset:17952
	ds_read_b32 v149, v59 offset:21120
	ds_read_b32 v157, v59 offset:22176
	ds_read_b32 v150, v59 offset:25344
	ds_read_b32 v158, v59 offset:26400
	ds_read_b32 v151, v59 offset:29568
	ds_read_b32 v159, v59 offset:30624
	s_waitcnt lgkmcnt(0)
	v_add_f32_e32 v144, v144, v145
	v_add_f32_e32 v152, v152, v153
	v_add_f32_e32 v144, v144, v146
	v_add_f32_e32 v152, v152, v154
	v_add_f32_e32 v144, v144, v147
	v_add_f32_e32 v152, v152, v155
	v_add_f32_e32 v144, v144, v148
	v_add_f32_e32 v152, v152, v156
	v_add_f32_e32 v144, v144, v149
	v_add_f32_e32 v152, v152, v157
	v_add_f32_e32 v144, v144, v150
	v_add_f32_e32 v152, v152, v158
	v_add_f32_e32 v144, v144, v151
	v_add_f32_e32 v152, v152, v159
	v_mul_f32_e32 v2, v49, v62
	v_mul_f32_e32 v3, v49, v63
	v_fmac_f32_e32 v2, v55, v144
	v_fmac_f32_e32 v3, v55, v152
	v_mul_f32_e32 v2, v52, v2
	v_mul_f32_e32 v3, v53, v3
	v_lshl_add_u32 v4, v9, 9, v8
	v_lshlrev_b32_e32 v4, 11, v4
	v_bfe_u32 v5, v2, 16, 1
	v_add3_u32 v5, v2, v5, s90
	global_store_short_d16_hi v4, v5, s[16:17]
	v_add_u32_e32 v4, 0x80000, v4
	v_bfe_u32 v5, v3, 16, 1
	v_add3_u32 v5, v3, v5, s90
	global_store_short_d16_hi v4, v5, s[16:17]
	s_mov_b32 s34, 0xc200000
	s_waitcnt lgkmcnt(0)
	s_barrier
	s_branch .LBB0_244
